# INB: the rows' pre-norm partial sums (non-reuse units) are LDS-DMA'd into free LDS during the K-loop and read with ds_read_b128 instead of 8 global loads + vmcnt(0) at the epilogue start; on top of v7
# speedup vs baseline: 1.0023x; 1.0022x over previous
; #define PG8_STAGE(bufoff, gbase, voff) do { _Pragma("unroll") for (int _i = 0; _i < 2; ++_i) \
;         __builtin_amdgcn_global_load_lds((const unsigned*)((const char*)(gbase) + (voff)[_i]), (PG8_LAS unsigned*)(lds + (bufoff) + ldsw + _i * 8192), 16, 0, 0); } while (0)
; #define PG8_LDA(dst, b, h) do { _Pragma("unroll") for (int m = 0; m < 4; ++m) _Pragma("unroll") for (int k = 0; k < 2; ++k) dst[m][k] = *(const PG8_LAS bf16x8*)(lds + PG8_SA(b, h) + aoff + m * 2048 + k * 1024); } while (0)
; #define PG8_LDB(dst, b, h) do { _Pragma("unroll") for (int n = 0; n < 2; ++n) _Pragma("unroll") for (int k = 0; k < 2; ++k) dst[n][k] = *(const PG8_LAS bf16x8*)(lds + PG8_SB(b, h) + boff + n * 2048 + k * 1024); } while (0)
; #define PG8_WAIT_V(n) asm volatile("s_waitcnt vmcnt(" #n ")" ::: "memory")
; #define PG8_WAIT_L(n) asm volatile("s_waitcnt lgkmcnt(" #n ")" ::: "memory")
; #define PG8_BAR __builtin_amdgcn_s_barrier()
; #define PG8_SCHED __builtin_amdgcn_sched_barrier(0)
;     __device__ __forceinline__ void operator()(const f32x4 (&acc)[2][2][4][2], const Unit& u, int wr, int wc, int fr, int fq, const bool reuse, PG8_LAS float* rscr, PG8_LAS const float* gains) const {
;     ...
;                     for (int m = 0; m < 4; ++m) { const int r = u.pm * BM + ai * HALF + wr * 64 + m * 16 + fr; rs4[ai][m] = *(const f32x4*)(rs + (size_t)(row_base + r) * 16 + 4 * fq); }
;     ...
;             PG8_LDB(B0, 0, 0); PG8_LDB(B1, 0, 1); PG8_SCHED; PG8_LDA(At, 0, 0); PG8_STAGE(PG8_SA(1, 1), a1 + hstep, voffA);
;             PG8_WAIT_V(8); PG8_WAIT_L(0); PG8_BAR; PG8_MMA(0, 0, At, B0); PG8_MMA(0, 1, At, B1); PG8_BAR; PG8_SCHED;
;             PG8_LDA(At, 0, 1); PG8_STAGE(PG8_SB(0, 0), b2, voffB); PG8_STAGE(PG8_SB(0, 1), b2 + hstepB, voffB); PG8_STAGE(PG8_SA(0, 0), a2, voffA);
;             PG8_WAIT_V(8); PG8_WAIT_L(0); PG8_BAR; PG8_MMA(1, 0, At, B0); PG8_MMA(1, 1, At, B1); PG8_BAR; PG8_SCHED;
;             PG8_LDB(B0, 1, 0); PG8_LDB(B1, 1, 1); PG8_SCHED; PG8_LDA(At, 1, 0); PG8_STAGE(PG8_SA(0, 1), a2 + hstep, voffA);
;             PG8_WAIT_V(8); PG8_WAIT_L(0); PG8_BAR; PG8_MMA(0, 0, At, B0); PG8_MMA(0, 1, At, B1); PG8_BAR; PG8_SCHED;
;             PG8_LDA(At, 1, 1); PG8_STAGE(PG8_SB(1, 0), b3, voffB); PG8_STAGE(PG8_SB(1, 1), b3 + hstepB, voffB); PG8_STAGE(PG8_SA(1, 0), a3, voffA);
;             PG8_WAIT_V(8); PG8_WAIT_L(0); PG8_BAR; PG8_MMA(1, 0, At, B0); PG8_MMA(1, 1, At, B1); PG8_BAR; PG8_SCHED;
.Lpkb_da:
	s_waitcnt lgkmcnt(0)
	s_barrier
	s_setprio 1
	s_waitcnt lgkmcnt(0)
	v_mfma_f32_16x16x32_f16 v[132:135], v[112:115], v[160:163], v[132:135]
	v_mfma_f32_16x16x32_f16 v[128:131], v[120:123], v[160:163], v[128:131]
	v_mfma_f32_16x16x32_f16 v[100:103], v[112:115], v[168:171], v[100:103]
	v_mfma_f32_16x16x32_f16 v[96:99], v[120:123], v[168:171], v[96:99]
	v_mfma_f32_16x16x32_f16 v[84:87], v[112:115], v[202:205], v[84:87]
	v_mfma_f32_16x16x32_f16 v[80:83], v[120:123], v[202:205], v[80:83]
	v_mfma_f32_16x16x32_f16 v[68:71], v[112:115], v[210:213], v[68:71]
	v_mfma_f32_16x16x32_f16 v[64:67], v[120:123], v[210:213], v[64:67]
	v_mfma_f32_16x16x32_f16 v[132:135], v[116:119], v[164:167], v[132:135]
	v_mfma_f32_16x16x32_f16 v[128:131], v[124:127], v[164:167], v[128:131]
	v_mfma_f32_16x16x32_f16 v[100:103], v[116:119], v[192:195], v[100:103]
	v_mfma_f32_16x16x32_f16 v[96:99], v[124:127], v[192:195], v[96:99]
	v_mfma_f32_16x16x32_f16 v[84:87], v[116:119], v[206:209], v[84:87]
	v_mfma_f32_16x16x32_f16 v[80:83], v[124:127], v[206:209], v[80:83]
	v_mfma_f32_16x16x32_f16 v[68:71], v[116:119], v[214:217], v[68:71]
	v_mfma_f32_16x16x32_f16 v[64:67], v[124:127], v[214:217], v[64:67]
	s_setprio 0
	s_setprio 1
	v_mfma_f32_16x16x32_f16 v[140:143], v[144:147], v[160:163], v[140:143]
	v_mfma_f32_16x16x32_f16 v[136:139], v[152:155], v[160:163], v[136:139]
	v_mfma_f32_16x16x32_f16 v[108:111], v[144:147], v[168:171], v[108:111]
	v_mfma_f32_16x16x32_f16 v[104:107], v[152:155], v[168:171], v[104:107]
	v_mfma_f32_16x16x32_f16 v[92:95], v[144:147], v[202:205], v[92:95]
	v_mfma_f32_16x16x32_f16 v[88:91], v[152:155], v[202:205], v[88:91]
	v_mfma_f32_16x16x32_f16 v[76:79], v[144:147], v[210:213], v[76:79]
	v_mfma_f32_16x16x32_f16 v[72:75], v[152:155], v[210:213], v[72:75]
	v_mfma_f32_16x16x32_f16 v[140:143], v[148:151], v[164:167], v[140:143]
	v_mfma_f32_16x16x32_f16 v[136:139], v[156:159], v[164:167], v[136:139]
	v_mfma_f32_16x16x32_f16 v[108:111], v[148:151], v[192:195], v[108:111]
	v_mfma_f32_16x16x32_f16 v[104:107], v[156:159], v[192:195], v[104:107]
	v_mfma_f32_16x16x32_f16 v[92:95], v[148:151], v[206:209], v[92:95]
	v_mfma_f32_16x16x32_f16 v[88:91], v[156:159], v[206:209], v[88:91]
	v_mfma_f32_16x16x32_f16 v[76:79], v[148:151], v[214:217], v[76:79]
	v_mfma_f32_16x16x32_f16 v[72:75], v[156:159], v[214:217], v[72:75]
	s_setprio 0
	s_barrier
	s_add_i32 s57, s51, s28
	v_lshl_add_u64 v[218:219], s[22:23], 0, v[174:175]
	s_mov_b32 m0, s57
	ds_read_b128 v[160:163], v200 offset:16384
	ds_read_b128 v[164:167], v200 offset:17408
	ds_read_b128 v[168:171], v200 offset:18432
	ds_read_b128 v[192:195], v200 offset:19456
	ds_read_b128 v[202:205], v200 offset:20480
	ds_read_b128 v[206:209], v200 offset:21504
	ds_read_b128 v[210:213], v200 offset:22528
	ds_read_b128 v[214:217], v200 offset:23552
	global_load_lds_dwordx4 v[218:219], off
	s_add_i32 m0, s57, 0x2000
	s_add_u32 s58, s22, 0x10000
	v_lshl_add_u64 v[220:221], s[22:23], 0, v[178:179]
	s_addc_u32 s59, s23, 0
	s_add_i32 s57, s52, s28
	global_load_lds_dwordx4 v[220:221], off
	v_lshl_add_u64 v[222:223], s[58:59], 0, v[174:175]
	s_mov_b32 m0, s57
	v_lshl_add_u64 v[224:225], s[26:27], 0, v[176:177]
	global_load_lds_dwordx4 v[222:223], off
	v_lshl_add_u64 v[222:223], s[58:59], 0, v[178:179]
	s_add_i32 m0, s57, 0x2000
	s_nop 0
	global_load_lds_dwordx4 v[222:223], off
	v_lshl_add_u64 v[222:223], s[26:27], 0, v[172:173]
	s_mov_b32 m0, s29
	s_nop 0
	global_load_lds_dwordx4 v[222:223], off
	s_mov_b32 m0, s41
	s_nop 0
	global_load_lds_dwordx4 v[224:225], off
	s_cmp_eq_u32 s56, 10
	s_cbranch_scc0 .Lrs_n
	s_cmp_lg_u32 s54, s38
	s_cbranch_scc0 .Lrs_n
	s_bitset1_b32 s101, 17
	s_lshl_b32 s32, s54, 8
	s_add_i32 s32, s32, s45
	s_bfe_u32 vcc_lo, s29, 0x2000a
	s_and_b32 vcc_hi, vcc_lo, 1
	s_lshl_b32 vcc_hi, vcc_hi, 5
	s_lshr_b32 m0, vcc_lo, 1
	s_lshl_b32 m0, m0, 7
	s_add_i32 vcc_hi, vcc_hi, m0
	s_add_i32 s32, s32, vcc_hi
	v_or_b32_e32 v228, s32, v196
	v_add_u32_e32 v230, 16, v228
	v_lshlrev_b32_e32 v228, 6, v228
	v_lshlrev_b32_e32 v230, 6, v230
	v_mov_b32_e32 v229, 0
	v_mov_b32_e32 v231, 0
	v_lshl_add_u64 v[228:229], v[228:229], 0, v[182:183]
	v_lshl_add_u64 v[230:231], v[230:231], 0, v[182:183]
	s_lshl_b32 vcc_lo, vcc_lo, 11
	s_lshr_b32 vcc_hi, s29, 12
	s_lshl_b32 vcc_hi, vcc_hi, 13
	s_add_i32 vcc_lo, vcc_lo, vcc_hi
	s_add_i32 m0, vcc_lo, 0x22000
	s_nop 0
	global_load_lds_dwordx4 v[228:229], off
	s_add_i32 m0, m0, 0x400
	s_nop 0
	global_load_lds_dwordx4 v[230:231], off
.Lrs_n:
	s_bfe_u32 vcc_lo, s101, 0x20010
	s_cmp_eq_u32 vcc_lo, 0
	s_cbranch_scc1 .Lpkb_w8b
	s_cmp_eq_u32 vcc_lo, 1
	s_cbranch_scc1 .Lpkb_w9b
	s_cmp_eq_u32 vcc_lo, 2
	s_cbranch_scc1 .Lpkb_w10b
	s_waitcnt vmcnt(11)
	s_branch .Lpkb_db

; #define PG8_STAGE(bufoff, gbase, voff) do { _Pragma("unroll") for (int _i = 0; _i < 2; ++_i) \
;         __builtin_amdgcn_global_load_lds((const unsigned*)((const char*)(gbase) + (voff)[_i]), (PG8_LAS unsigned*)(lds + (bufoff) + ldsw + _i * 8192), 16, 0, 0); } while (0)
; #define PG8_LDA(dst, b, h) do { _Pragma("unroll") for (int m = 0; m < 4; ++m) _Pragma("unroll") for (int k = 0; k < 2; ++k) dst[m][k] = *(const PG8_LAS bf16x8*)(lds + PG8_SA(b, h) + aoff + m * 2048 + k * 1024); } while (0)
; #define PG8_LDB(dst, b, h) do { _Pragma("unroll") for (int n = 0; n < 2; ++n) _Pragma("unroll") for (int k = 0; k < 2; ++k) dst[n][k] = *(const PG8_LAS bf16x8*)(lds + PG8_SB(b, h) + boff + n * 2048 + k * 1024); } while (0)
; #define PG8_WAIT_V(n) asm volatile("s_waitcnt vmcnt(" #n ")" ::: "memory")
; #define PG8_WAIT_L(n) asm volatile("s_waitcnt lgkmcnt(" #n ")" ::: "memory")
; #define PG8_BAR __builtin_amdgcn_s_barrier()
; #define PG8_SCHED __builtin_amdgcn_sched_barrier(0)
;     ...
;             PG8_LDB(B0, 0, 0); PG8_LDB(B1, 0, 1); PG8_SCHED; PG8_LDA(At, 0, 0); PG8_STAGE(PG8_SA(1, 1), a1 + hstep, voffA);
;             PG8_WAIT_V(8); PG8_WAIT_L(0); PG8_BAR; PG8_MMA(0, 0, At, B0); PG8_MMA(0, 1, At, B1); PG8_BAR; PG8_SCHED;
;             PG8_LDA(At, 0, 1); PG8_STAGE(PG8_SB(0, 0), b2, voffB); PG8_STAGE(PG8_SB(0, 1), b2 + hstepB, voffB); PG8_STAGE(PG8_SA(0, 0), a2, voffA);
;             PG8_WAIT_V(8); PG8_WAIT_L(0); PG8_BAR; PG8_MMA(1, 0, At, B0); PG8_MMA(1, 1, At, B1); PG8_BAR; PG8_SCHED;
;             PG8_LDB(B0, 1, 0); PG8_LDB(B1, 1, 1); PG8_SCHED; PG8_LDA(At, 1, 0); PG8_STAGE(PG8_SA(0, 1), a2 + hstep, voffA);
;             PG8_WAIT_V(8); PG8_WAIT_L(0); PG8_BAR; PG8_MMA(0, 0, At, B0); PG8_MMA(0, 1, At, B1); PG8_BAR; PG8_SCHED;
;             PG8_LDA(At, 1, 1); PG8_STAGE(PG8_SB(1, 0), b3, voffB); PG8_STAGE(PG8_SB(1, 1), b3 + hstepB, voffB); PG8_STAGE(PG8_SA(1, 0), a3, voffA);
;             PG8_WAIT_V(8); PG8_WAIT_L(0); PG8_BAR; PG8_MMA(1, 0, At, B0); PG8_MMA(1, 1, At, B1); PG8_BAR; PG8_SCHED;
.Lpkb_db:
	s_waitcnt lgkmcnt(0)
	s_barrier
	s_setprio 1
	s_waitcnt lgkmcnt(0)
	v_mfma_f32_16x16x32_f16 v[52:55], v[112:115], v[160:163], v[52:55]
	v_mfma_f32_16x16x32_f16 v[48:51], v[120:123], v[160:163], v[48:51]
	v_mfma_f32_16x16x32_f16 v[36:39], v[112:115], v[168:171], v[36:39]
	v_mfma_f32_16x16x32_f16 v[32:35], v[120:123], v[168:171], v[32:35]
	v_mfma_f32_16x16x32_f16 v[20:23], v[112:115], v[202:205], v[20:23]
	v_mfma_f32_16x16x32_f16 v[16:19], v[120:123], v[202:205], v[16:19]
	v_mfma_f32_16x16x32_f16 v[4:7], v[112:115], v[210:213], v[4:7]
	v_mfma_f32_16x16x32_f16 v[0:3], v[120:123], v[210:213], v[0:3]
	v_mfma_f32_16x16x32_f16 v[52:55], v[116:119], v[164:167], v[52:55]
	v_mfma_f32_16x16x32_f16 v[48:51], v[124:127], v[164:167], v[48:51]
	v_mfma_f32_16x16x32_f16 v[36:39], v[116:119], v[192:195], v[36:39]
	v_mfma_f32_16x16x32_f16 v[32:35], v[124:127], v[192:195], v[32:35]
	v_mfma_f32_16x16x32_f16 v[20:23], v[116:119], v[206:209], v[20:23]
	v_mfma_f32_16x16x32_f16 v[16:19], v[124:127], v[206:209], v[16:19]
	v_mfma_f32_16x16x32_f16 v[4:7], v[116:119], v[214:217], v[4:7]
	v_mfma_f32_16x16x32_f16 v[0:3], v[124:127], v[214:217], v[0:3]
	s_setprio 0
	s_setprio 1
	v_mfma_f32_16x16x32_f16 v[60:63], v[144:147], v[160:163], v[60:63]
	v_mfma_f32_16x16x32_f16 v[56:59], v[152:155], v[160:163], v[56:59]
	v_mfma_f32_16x16x32_f16 v[44:47], v[144:147], v[168:171], v[44:47]
	v_mfma_f32_16x16x32_f16 v[40:43], v[152:155], v[168:171], v[40:43]
	v_mfma_f32_16x16x32_f16 v[28:31], v[144:147], v[202:205], v[28:31]
	v_mfma_f32_16x16x32_f16 v[24:27], v[152:155], v[202:205], v[24:27]
	v_mfma_f32_16x16x32_f16 v[12:15], v[144:147], v[210:213], v[12:15]
	v_mfma_f32_16x16x32_f16 v[8:11], v[152:155], v[210:213], v[8:11]
	v_mfma_f32_16x16x32_f16 v[60:63], v[148:151], v[164:167], v[60:63]
	v_mfma_f32_16x16x32_f16 v[56:59], v[156:159], v[164:167], v[56:59]
	v_mfma_f32_16x16x32_f16 v[44:47], v[148:151], v[192:195], v[44:47]
	v_mfma_f32_16x16x32_f16 v[40:43], v[156:159], v[192:195], v[40:43]
	v_mfma_f32_16x16x32_f16 v[28:31], v[148:151], v[206:209], v[28:31]
	v_mfma_f32_16x16x32_f16 v[24:27], v[156:159], v[206:209], v[24:27]
	v_mfma_f32_16x16x32_f16 v[12:15], v[148:151], v[214:217], v[12:15]
	v_mfma_f32_16x16x32_f16 v[8:11], v[156:159], v[214:217], v[8:11]
	s_setprio 0
	s_barrier
	s_add_i32 s57, 0, 0x18000
	s_add_i32 s58, 0, 0x1c000
	v_add_u32_e32 v124, s57, v197
	v_add_u32_e32 v156, s58, v197
	ds_read_b128 v[112:115], v124
	ds_read_b128 v[116:119], v124 offset:1024
	ds_read_b128 v[120:123], v124 offset:2048
	ds_read_b128 v[124:127], v124 offset:3072
	ds_read_b128 v[144:147], v156
	ds_read_b128 v[148:151], v156 offset:1024
	ds_read_b128 v[152:155], v156 offset:2048
	ds_read_b128 v[156:159], v156 offset:3072
	s_add_u32 s26, s26, 0x40000
	s_addc_u32 s27, s27, 0
	s_mov_b32 m0, s42
	v_lshl_add_u64 v[226:227], s[26:27], 0, v[172:173]
	ds_read_b128 v[160:163], v200 offset:32768
	ds_read_b128 v[164:167], v200 offset:33792
	ds_read_b128 v[168:171], v200 offset:34816
	ds_read_b128 v[192:195], v200 offset:35840
	ds_read_b128 v[202:205], v200 offset:36864
	ds_read_b128 v[206:209], v200 offset:37888
	ds_read_b128 v[210:213], v200 offset:38912
	ds_read_b128 v[214:217], v200 offset:39936
	global_load_lds_dwordx4 v[226:227], off
	v_lshl_add_u64 v[226:227], s[26:27], 0, v[176:177]
	s_mov_b32 m0, s43
	s_nop 0
	global_load_lds_dwordx4 v[226:227], off
	s_bfe_u32 vcc_lo, s101, 0x20010
	s_cmp_eq_u32 vcc_lo, 0
	s_cbranch_scc1 .Lpkb_w8c
	s_cmp_eq_u32 vcc_lo, 1
	s_cbranch_scc1 .Lpkb_w9c
	s_cmp_eq_u32 vcc_lo, 2
	s_cbranch_scc1 .Lpkb_w10c
	s_waitcnt vmcnt(11)
	s_branch .Lpkb_dc

; #define PG8_STAGE(bufoff, gbase, voff) do { _Pragma("unroll") for (int _i = 0; _i < 2; ++_i) \
;         __builtin_amdgcn_global_load_lds((const unsigned*)((const char*)(gbase) + (voff)[_i]), (PG8_LAS unsigned*)(lds + (bufoff) + ldsw + _i * 8192), 16, 0, 0); } while (0)
; #define PG8_LDA(dst, b, h) do { _Pragma("unroll") for (int m = 0; m < 4; ++m) _Pragma("unroll") for (int k = 0; k < 2; ++k) dst[m][k] = *(const PG8_LAS bf16x8*)(lds + PG8_SA(b, h) + aoff + m * 2048 + k * 1024); } while (0)
; #define PG8_LDB(dst, b, h) do { _Pragma("unroll") for (int n = 0; n < 2; ++n) _Pragma("unroll") for (int k = 0; k < 2; ++k) dst[n][k] = *(const PG8_LAS bf16x8*)(lds + PG8_SB(b, h) + boff + n * 2048 + k * 1024); } while (0)
; #define PG8_WAIT_V(n) asm volatile("s_waitcnt vmcnt(" #n ")" ::: "memory")
; #define PG8_WAIT_L(n) asm volatile("s_waitcnt lgkmcnt(" #n ")" ::: "memory")
; #define PG8_BAR __builtin_amdgcn_s_barrier()
; #define PG8_SCHED __builtin_amdgcn_sched_barrier(0)
;     ...
;             PG8_LDB(B0, 0, 0); PG8_LDB(B1, 0, 1); PG8_SCHED; PG8_LDA(At, 0, 0); PG8_STAGE(PG8_SA(1, 1), a1 + hstep, voffA);
;             PG8_WAIT_V(8); PG8_WAIT_L(0); PG8_BAR; PG8_MMA(0, 0, At, B0); PG8_MMA(0, 1, At, B1); PG8_BAR; PG8_SCHED;
;             PG8_LDA(At, 0, 1); PG8_STAGE(PG8_SB(0, 0), b2, voffB); PG8_STAGE(PG8_SB(0, 1), b2 + hstepB, voffB); PG8_STAGE(PG8_SA(0, 0), a2, voffA);
;             PG8_WAIT_V(8); PG8_WAIT_L(0); PG8_BAR; PG8_MMA(1, 0, At, B0); PG8_MMA(1, 1, At, B1); PG8_BAR; PG8_SCHED;
;             PG8_LDB(B0, 1, 0); PG8_LDB(B1, 1, 1); PG8_SCHED; PG8_LDA(At, 1, 0); PG8_STAGE(PG8_SA(0, 1), a2 + hstep, voffA);
;             PG8_WAIT_V(8); PG8_WAIT_L(0); PG8_BAR; PG8_MMA(0, 0, At, B0); PG8_MMA(0, 1, At, B1); PG8_BAR; PG8_SCHED;
;             PG8_LDA(At, 1, 1); PG8_STAGE(PG8_SB(1, 0), b3, voffB); PG8_STAGE(PG8_SB(1, 1), b3 + hstepB, voffB); PG8_STAGE(PG8_SA(1, 0), a3, voffA);
;             PG8_WAIT_V(8); PG8_WAIT_L(0); PG8_BAR; PG8_MMA(1, 0, At, B0); PG8_MMA(1, 1, At, B1); PG8_BAR; PG8_SCHED;
.Lpkb_dc:
	s_waitcnt lgkmcnt(0)
	s_barrier
	s_setprio 1
	s_waitcnt lgkmcnt(0)
	v_mfma_f32_16x16x32_f16 v[132:135], v[112:115], v[160:163], v[132:135]
	v_mfma_f32_16x16x32_f16 v[128:131], v[120:123], v[160:163], v[128:131]
	v_mfma_f32_16x16x32_f16 v[100:103], v[112:115], v[168:171], v[100:103]
	v_mfma_f32_16x16x32_f16 v[96:99], v[120:123], v[168:171], v[96:99]
	v_mfma_f32_16x16x32_f16 v[84:87], v[112:115], v[202:205], v[84:87]
	v_mfma_f32_16x16x32_f16 v[80:83], v[120:123], v[202:205], v[80:83]
	v_mfma_f32_16x16x32_f16 v[68:71], v[112:115], v[210:213], v[68:71]
	v_mfma_f32_16x16x32_f16 v[64:67], v[120:123], v[210:213], v[64:67]
	v_mfma_f32_16x16x32_f16 v[132:135], v[116:119], v[164:167], v[132:135]
	v_mfma_f32_16x16x32_f16 v[128:131], v[124:127], v[164:167], v[128:131]
	v_mfma_f32_16x16x32_f16 v[100:103], v[116:119], v[192:195], v[100:103]
	v_mfma_f32_16x16x32_f16 v[96:99], v[124:127], v[192:195], v[96:99]
	v_mfma_f32_16x16x32_f16 v[84:87], v[116:119], v[206:209], v[84:87]
	v_mfma_f32_16x16x32_f16 v[80:83], v[124:127], v[206:209], v[80:83]
	v_mfma_f32_16x16x32_f16 v[68:71], v[116:119], v[214:217], v[68:71]
	v_mfma_f32_16x16x32_f16 v[64:67], v[124:127], v[214:217], v[64:67]
	s_setprio 0
	s_setprio 1
	v_mfma_f32_16x16x32_f16 v[140:143], v[144:147], v[160:163], v[140:143]
	v_mfma_f32_16x16x32_f16 v[136:139], v[152:155], v[160:163], v[136:139]
	v_mfma_f32_16x16x32_f16 v[108:111], v[144:147], v[168:171], v[108:111]
	v_mfma_f32_16x16x32_f16 v[104:107], v[152:155], v[168:171], v[104:107]
	v_mfma_f32_16x16x32_f16 v[92:95], v[144:147], v[202:205], v[92:95]
	v_mfma_f32_16x16x32_f16 v[88:91], v[152:155], v[202:205], v[88:91]
	v_mfma_f32_16x16x32_f16 v[76:79], v[144:147], v[210:213], v[76:79]
	v_mfma_f32_16x16x32_f16 v[72:75], v[152:155], v[210:213], v[72:75]
	v_mfma_f32_16x16x32_f16 v[140:143], v[148:151], v[164:167], v[140:143]
	v_mfma_f32_16x16x32_f16 v[136:139], v[156:159], v[164:167], v[136:139]
	v_mfma_f32_16x16x32_f16 v[108:111], v[148:151], v[192:195], v[108:111]
	v_mfma_f32_16x16x32_f16 v[104:107], v[156:159], v[192:195], v[104:107]
	v_mfma_f32_16x16x32_f16 v[92:95], v[148:151], v[206:209], v[92:95]
	v_mfma_f32_16x16x32_f16 v[88:91], v[156:159], v[206:209], v[88:91]
	v_mfma_f32_16x16x32_f16 v[76:79], v[148:151], v[214:217], v[76:79]
	v_mfma_f32_16x16x32_f16 v[72:75], v[156:159], v[214:217], v[72:75]
	s_setprio 0
	s_barrier
	s_add_i32 s26, s57, s28
	v_lshl_add_u64 v[218:219], v[218:219], 0, s[10:11]
	s_mov_b32 m0, s26
	ds_read_b128 v[160:163], v200 offset:49152
	ds_read_b128 v[164:167], v200 offset:50176
	ds_read_b128 v[168:171], v200 offset:51200
	ds_read_b128 v[192:195], v200 offset:52224
	ds_read_b128 v[202:205], v200 offset:53248
	ds_read_b128 v[206:209], v200 offset:54272
	ds_read_b128 v[210:213], v200 offset:55296
	ds_read_b128 v[214:217], v200 offset:56320
	global_load_lds_dwordx4 v[218:219], off
	s_add_i32 m0, s26, 0x2000
	s_add_u32 s22, s22, 0x10080
	v_lshl_add_u64 v[218:219], v[220:221], 0, s[10:11]
	s_addc_u32 s23, s23, 0
	s_add_i32 s26, s58, s28
	global_load_lds_dwordx4 v[218:219], off
	v_lshl_add_u64 v[218:219], s[22:23], 0, v[174:175]
	s_mov_b32 m0, s26
	s_nop 0
	global_load_lds_dwordx4 v[218:219], off
	v_lshl_add_u64 v[218:219], s[22:23], 0, v[178:179]
	s_add_i32 m0, s26, 0x2000
	s_nop 0
	global_load_lds_dwordx4 v[218:219], off
	v_lshl_add_u64 v[218:219], v[222:223], 0, s[10:11]
	s_mov_b32 m0, s48
	s_nop 0
	global_load_lds_dwordx4 v[218:219], off
	v_lshl_add_u64 v[218:219], v[224:225], 0, s[10:11]
	s_mov_b32 m0, s49
	s_nop 0
	global_load_lds_dwordx4 v[218:219], off
	s_bitcmp1_b32 s101, 17
	s_cbranch_scc0 .Lpkb_w8e
	s_waitcnt vmcnt(10)
	s_branch .Lpkb_de

; #define PG8_STAGE(bufoff, gbase, voff) do { _Pragma("unroll") for (int _i = 0; _i < 2; ++_i) \
;         __builtin_amdgcn_global_load_lds((const unsigned*)((const char*)(gbase) + (voff)[_i]), (PG8_LAS unsigned*)(lds + (bufoff) + ldsw + _i * 8192), 16, 0, 0); } while (0)
; #define PG8_LDA(dst, b, h) do { _Pragma("unroll") for (int m = 0; m < 4; ++m) _Pragma("unroll") for (int k = 0; k < 2; ++k) dst[m][k] = *(const PG8_LAS bf16x8*)(lds + PG8_SA(b, h) + aoff + m * 2048 + k * 1024); } while (0)
; #define PG8_WAIT_V(n) asm volatile("s_waitcnt vmcnt(" #n ")" ::: "memory")
; #define PG8_WAIT_L(n) asm volatile("s_waitcnt lgkmcnt(" #n ")" ::: "memory")
; #define PG8_BAR __builtin_amdgcn_s_barrier()
; #define PG8_SCHED __builtin_amdgcn_sched_barrier(0)
;     ...
;             PG8_WAIT_V(8); PG8_WAIT_L(0); PG8_BAR; PG8_MMA(0, 0, At, B0); PG8_MMA(0, 1, At, B1); PG8_BAR; PG8_SCHED;
;             PG8_LDA(At, 1, 1); PG8_STAGE(PG8_SB(1, 0), b3, voffB); PG8_STAGE(PG8_SB(1, 1), b3 + hstepB, voffB); PG8_STAGE(PG8_SA(1, 0), a3, voffA);
;             PG8_WAIT_V(8); PG8_WAIT_L(0); PG8_BAR; PG8_MMA(1, 0, At, B0); PG8_MMA(1, 1, At, B1); PG8_BAR; PG8_SCHED;
;         }
.Lpkb_de:
	s_waitcnt lgkmcnt(0)
	s_barrier
	s_setprio 1
	s_waitcnt lgkmcnt(0)
	v_mfma_f32_16x16x32_f16 v[52:55], v[112:115], v[160:163], v[52:55]
	v_mfma_f32_16x16x32_f16 v[48:51], v[120:123], v[160:163], v[48:51]
	v_mfma_f32_16x16x32_f16 v[36:39], v[112:115], v[168:171], v[36:39]
	v_mfma_f32_16x16x32_f16 v[32:35], v[120:123], v[168:171], v[32:35]
	v_mfma_f32_16x16x32_f16 v[20:23], v[112:115], v[202:205], v[20:23]
	v_mfma_f32_16x16x32_f16 v[16:19], v[120:123], v[202:205], v[16:19]
	v_mfma_f32_16x16x32_f16 v[4:7], v[112:115], v[210:213], v[4:7]
	v_mfma_f32_16x16x32_f16 v[0:3], v[120:123], v[210:213], v[0:3]
	v_mfma_f32_16x16x32_f16 v[52:55], v[116:119], v[164:167], v[52:55]
	v_mfma_f32_16x16x32_f16 v[48:51], v[124:127], v[164:167], v[48:51]
	v_mfma_f32_16x16x32_f16 v[36:39], v[116:119], v[192:195], v[36:39]
	v_mfma_f32_16x16x32_f16 v[32:35], v[124:127], v[192:195], v[32:35]
	v_mfma_f32_16x16x32_f16 v[20:23], v[116:119], v[206:209], v[20:23]
	v_mfma_f32_16x16x32_f16 v[16:19], v[124:127], v[206:209], v[16:19]
	v_mfma_f32_16x16x32_f16 v[4:7], v[116:119], v[214:217], v[4:7]
	v_mfma_f32_16x16x32_f16 v[0:3], v[124:127], v[214:217], v[0:3]
	s_setprio 0
	s_setprio 1
	v_mfma_f32_16x16x32_f16 v[60:63], v[144:147], v[160:163], v[60:63]
	v_mfma_f32_16x16x32_f16 v[56:59], v[152:155], v[160:163], v[56:59]
	v_mfma_f32_16x16x32_f16 v[44:47], v[144:147], v[168:171], v[44:47]
	v_mfma_f32_16x16x32_f16 v[40:43], v[152:155], v[168:171], v[40:43]
	v_mfma_f32_16x16x32_f16 v[28:31], v[144:147], v[202:205], v[28:31]
	v_mfma_f32_16x16x32_f16 v[24:27], v[152:155], v[202:205], v[24:27]
	v_mfma_f32_16x16x32_f16 v[12:15], v[144:147], v[210:213], v[12:15]
	v_mfma_f32_16x16x32_f16 v[8:11], v[152:155], v[210:213], v[8:11]
	v_mfma_f32_16x16x32_f16 v[60:63], v[148:151], v[164:167], v[60:63]
	v_mfma_f32_16x16x32_f16 v[56:59], v[156:159], v[164:167], v[56:59]
	v_mfma_f32_16x16x32_f16 v[44:47], v[148:151], v[192:195], v[44:47]
	v_mfma_f32_16x16x32_f16 v[40:43], v[156:159], v[192:195], v[40:43]
	v_mfma_f32_16x16x32_f16 v[28:31], v[148:151], v[206:209], v[28:31]
	v_mfma_f32_16x16x32_f16 v[24:27], v[156:159], v[206:209], v[24:27]
	v_mfma_f32_16x16x32_f16 v[12:15], v[148:151], v[214:217], v[12:15]
	v_mfma_f32_16x16x32_f16 v[8:11], v[156:159], v[214:217], v[8:11]
	s_setprio 0
	s_barrier
	s_bitcmp1_b32 s101, 16
	s_cbranch_scc0 .Lpkb_t
	s_sub_u32 s101, s101, 1
.Lpkb_t:
	s_and_b32 s101, s101, 0xff
	s_add_i32 s56, s56, 2
	s_add_u32 s24, s24, 0x100
	s_addc_u32 s25, s25, 0
	s_add_u32 s39, s39, 0x100
	s_addc_u32 s55, s55, 0
	s_cmp_gt_u32 s56, 13
	s_cbranch_scc0 .LBB0_532
	s_and_b64 vcc, exec, s[14:15]
	s_cbranch_vccz .LBB0_535
	s_barrier

; __device__ __forceinline__ float sum_x16(float v) { float a, b; swap16(v, a, b); return a + b; }
; __device__ __forceinline__ float sum_x32(float v) { float a, b; swap32(v, a, b); return a + b; }
;     __device__ __forceinline__ void operator()(const f32x4 (&acc)[2][2][4][2], const Unit& u, int wr, int wc, int fr, int fq, const bool reuse, PG8_LAS float* rscr, PG8_LAS const float* gains) const {
;     ...
;                 f32x4 rs4[2][4];
; #pragma unroll
;                 for (int ai = 0; ai < 2; ++ai)
; #pragma unroll
;                     for (int m = 0; m < 4; ++m) { const int r = u.pm * BM + ai * HALF + wr * 64 + m * 16 + fr; rs4[ai][m] = *(const f32x4*)(rs + (size_t)(row_base + r) * 16 + 4 * fq); }
; #pragma unroll
;                 for (int ai = 0; ai < 2; ++ai)
; #pragma unroll
;                     for (int m = 0; m < 4; ++m) { const f32x4 pp = rs4[ai][m]; float s = (pp[0] + pp[1]) + (pp[2] + pp[3]); s = sum_x16(s); s = sum_x32(s);
;                         rsvv[ai][m] = __builtin_amdgcn_rsqf(s * (1.0f / 1024.0f) + RMS_EPS); if (fq == 0) rsl[(ai * 4 + m) * 16] = rsvv[ai][m]; }
;             }
.LBB0_541:
	s_cmp_lg_u32 s54, s38
	s_mov_b64 s[26:27], -1
	s_cbranch_scc0 .LBB0_559
	v_mbcnt_lo_u32_b32 v144, -1, 0
	v_mbcnt_hi_u32_b32 v144, -1, v144
	s_lshr_b32 s2, s29, 12
	s_lshl_b32 s2, s2, 13
	s_add_i32 s2, s2, 0x22000
	v_lshl_add_u32 v144, v144, 4, s2
	ds_read_b128 v[202:205], v144
	ds_read_b128 v[168:171], v144 offset:1024
	ds_read_b128 v[164:167], v144 offset:2048
	ds_read_b128 v[160:163], v144 offset:3072
	ds_read_b128 v[156:159], v144 offset:4096
	ds_read_b128 v[152:155], v144 offset:5120
	ds_read_b128 v[148:151], v144 offset:6144
	ds_read_b128 v[144:147], v144 offset:7168
	s_waitcnt lgkmcnt(0)
	v_add_f32_e32 v194, v202, v203
	v_add_f32_e32 v195, v204, v205
	v_add_f32_e32 v194, v194, v195
	v_mov_b32_e32 v195, v194
	s_nop 1
	v_permlane16_swap_b32_e32 v194, v195
	v_add_f32_e32 v194, v194, v195
	v_mov_b32_e32 v195, v194
	s_nop 1
	v_permlane32_swap_b32_e32 v194, v195
	v_add_f32_e32 v194, v194, v195
	v_fmamk_f32 v194, v194, 0x3a800000, v201
	v_rsq_f32_e32 v194, v194
	s_and_saveexec_b64 s[26:27], s[34:35]
	v_add_u32_e32 v195, s50, v198
	ds_write_b32 v195, v194
	s_or_b64 exec, exec, s[26:27]
	v_add_f32_e32 v168, v168, v169
	v_add_f32_e32 v169, v170, v171
	v_add_f32_e32 v168, v168, v169
	v_mov_b32_e32 v169, v168
	s_nop 1
	v_permlane16_swap_b32_e32 v168, v169
	v_add_f32_e32 v168, v168, v169
	v_mov_b32_e32 v169, v168
	s_nop 1
	v_permlane32_swap_b32_e32 v168, v169
	v_add_f32_e32 v168, v168, v169
	v_fmamk_f32 v168, v168, 0x3a800000, v201
	v_rsq_f32_e32 v168, v168
	s_and_saveexec_b64 s[26:27], s[34:35]
	v_add_u32_e32 v169, s50, v198
	ds_write_b32 v169, v168 offset:64
	s_or_b64 exec, exec, s[26:27]
	v_add_f32_e32 v164, v164, v165
	v_add_f32_e32 v165, v166, v167
	v_add_f32_e32 v164, v164, v165
	v_mov_b32_e32 v165, v164
	s_nop 1
	v_permlane16_swap_b32_e32 v164, v165
	v_add_f32_e32 v164, v164, v165
	v_mov_b32_e32 v165, v164
	s_nop 1
	v_permlane32_swap_b32_e32 v164, v165
	v_add_f32_e32 v164, v164, v165
	v_fmamk_f32 v164, v164, 0x3a800000, v201
	v_rsq_f32_e32 v164, v164
	s_and_saveexec_b64 s[26:27], s[34:35]
	v_add_u32_e32 v165, s50, v198
	ds_write_b32 v165, v164 offset:128
	s_or_b64 exec, exec, s[26:27]
	v_add_f32_e32 v160, v160, v161
	v_add_f32_e32 v161, v162, v163
	v_add_f32_e32 v160, v160, v161
	v_mov_b32_e32 v161, v160
	s_nop 1
	v_permlane16_swap_b32_e32 v160, v161
	v_add_f32_e32 v160, v160, v161
	v_mov_b32_e32 v161, v160
	s_nop 1
	v_permlane32_swap_b32_e32 v160, v161
	v_add_f32_e32 v160, v160, v161
	v_fmamk_f32 v160, v160, 0x3a800000, v201
	v_rsq_f32_e32 v160, v160
	s_and_saveexec_b64 s[26:27], s[34:35]
	v_add_u32_e32 v161, s50, v198
	ds_write_b32 v161, v160 offset:192
	s_or_b64 exec, exec, s[26:27]
	v_add_f32_e32 v156, v156, v157
	v_add_f32_e32 v157, v158, v159
	v_add_f32_e32 v156, v156, v157
	v_mov_b32_e32 v157, v156
	s_nop 1
	v_permlane16_swap_b32_e32 v156, v157
	v_add_f32_e32 v156, v156, v157
	v_mov_b32_e32 v157, v156
	s_nop 1
	v_permlane32_swap_b32_e32 v156, v157
	v_add_f32_e32 v156, v156, v157
	v_fmamk_f32 v156, v156, 0x3a800000, v201
	v_rsq_f32_e32 v156, v156
	s_and_saveexec_b64 s[26:27], s[34:35]
	v_add_u32_e32 v157, s50, v198
	ds_write_b32 v157, v156 offset:256
	s_or_b64 exec, exec, s[26:27]
	v_add_f32_e32 v152, v152, v153
	v_add_f32_e32 v153, v154, v155
	v_add_f32_e32 v152, v152, v153
	v_mov_b32_e32 v153, v152
	s_nop 1
	v_permlane16_swap_b32_e32 v152, v153
	v_add_f32_e32 v152, v152, v153
	v_mov_b32_e32 v153, v152
	s_nop 1
	v_permlane32_swap_b32_e32 v152, v153
	v_add_f32_e32 v152, v152, v153
	v_fmamk_f32 v152, v152, 0x3a800000, v201
	v_rsq_f32_e32 v152, v152
	s_and_saveexec_b64 s[26:27], s[34:35]
	v_add_u32_e32 v153, s50, v198
	ds_write_b32 v153, v152 offset:320
	s_or_b64 exec, exec, s[26:27]
	v_add_f32_e32 v148, v148, v149
	v_add_f32_e32 v149, v150, v151
	v_add_f32_e32 v148, v148, v149
	v_mov_b32_e32 v149, v148
	s_nop 1
	v_permlane16_swap_b32_e32 v148, v149
	v_add_f32_e32 v148, v148, v149
	v_mov_b32_e32 v149, v148
	s_nop 1
	v_permlane32_swap_b32_e32 v148, v149
	v_add_f32_e32 v148, v148, v149
	v_fmamk_f32 v148, v148, 0x3a800000, v201
	v_rsq_f32_e32 v148, v148
	s_and_saveexec_b64 s[26:27], s[34:35]
	v_add_u32_e32 v149, s50, v198
	ds_write_b32 v149, v148 offset:384
	s_or_b64 exec, exec, s[26:27]
	v_add_f32_e32 v144, v144, v145
	v_add_f32_e32 v145, v146, v147
	v_add_f32_e32 v144, v144, v145
	v_mov_b32_e32 v145, v144
	s_nop 1
	v_permlane16_swap_b32_e32 v144, v145
	v_add_f32_e32 v144, v144, v145
	v_mov_b32_e32 v145, v144
	s_nop 1
	v_permlane32_swap_b32_e32 v144, v145
	v_add_f32_e32 v144, v144, v145
	v_fmamk_f32 v144, v144, 0x3a800000, v201
	v_rsq_f32_e32 v144, v144
	s_and_saveexec_b64 s[26:27], s[34:35]
	v_add_u32_e32 v145, s50, v198
	ds_write_b32 v145, v144 offset:448
	s_or_b64 exec, exec, s[26:27]
	s_branch .LBB0_561
